# as previous, next KV tile global loads issued right after the LDS staging writes (before the tile barrier) instead of at the top of the next iteration
# baseline (speedup 1.0000x reference)
; template <int DQK, int DV, int RH, bool NEGM> ...
;     ...
;     const int NT = nkv / 64;
;     AT_GLOAD(0); AT_LSTORE(0, 0); __syncthreads();
;     int vs_prev = 2, vs_cur = 0, vs_next = 1;
;     if (!grpB) {
;         for (int t = 0; t < NT; ++t) {
;             const int kb = t & 1;
;             if (t + 1 < NT) AT_GLOAD(t + 1);
.LBB0_881:
	s_or_b64 exec, exec, s[42:43]
	v_pk_add_f32 v[48:49], v[48:49], v[54:55]
	v_pk_add_f32 v[64:65], v[128:129], v[64:65]
	v_pk_add_f32 v[48:49], v[58:59], v[48:49] op_sel_hi:[0,1]
	v_pk_add_f32 v[52:53], v[52:53], v[56:57]
	v_pk_add_f32 v[48:49], v[64:65], v[48:49]
	v_pk_add_f32 v[70:71], v[118:119], v[70:71]
	v_pk_add_f32 v[48:49], v[52:53], v[48:49]
	v_add_u32_e32 v54, v136, v135
	v_pk_add_f32 v[150:151], v[70:71], v[48:49]
	v_add_u32_e32 v48, 0x8c00, v166
	s_waitcnt vmcnt(0)
	ds_write2_b64 v48, v[74:75], v[76:77] offset1:2
	v_mul_lo_u32 v48, v54, 12
	v_sub_u32_e32 v52, v133, v48
	s_lshr_b32 s21, s61, 4
	v_lshlrev_b32_e32 v48, 3, v52
	v_lshlrev_b32_e32 v175, 4, v52
	v_mov_b64_e32 v[52:53], s[40:41]
	s_and_b32 s42, s21, 7
	v_mul_lo_u32 v174, v54, s56
	v_mad_i64_i32 v[54:55], s[40:41], v54, s51, v[52:53]
	v_pk_add_f32 v[50:51], v[50:51], v[62:63]
	v_ashrrev_i32_e32 v49, 31, v48
	v_mad_u64_u32 v[54:55], s[40:41], s42, v163, v[54:55]
	v_pk_add_f32 v[66:67], v[130:131], v[66:67]
	v_pk_add_f32 v[50:51], v[58:59], v[50:51] op_sel_hi:[0,1]
	v_lshl_add_u64 v[48:49], v[48:49], 1, v[54:55]
	v_pk_add_f32 v[56:57], v[116:117], v[68:69]
	v_pk_add_f32 v[50:51], v[66:67], v[50:51]
	v_mov_b32_e32 v154, v48
	v_mad_i64_i32 v[48:49], s[40:41], v59, s51, v[52:53]
	v_pk_add_f32 v[60:61], v[60:61], v[72:73]
	v_pk_add_f32 v[50:51], v[56:57], v[50:51]
	s_lshl_b32 s43, s42, 6
	v_mad_u64_u32 v[48:49], s[40:41], s42, v163, v[48:49]
	v_pk_add_f32 v[152:153], v[60:61], v[50:51]
	v_lshlrev_b32_e32 v50, 3, v112
	s_add_i32 s40, s47, s43
	v_ashrrev_i32_e32 v51, 31, v50
	s_ashr_i32 s41, s40, 31
	v_lshl_add_u64 v[48:49], v[50:51], 1, v[48:49]
	s_lshl_b64 s[40:41], s[40:41], 13
	v_and_b32_e32 v50, 7, v132
	v_mov_b32_e32 v156, v48
	v_lshl_add_u64 v[48:49], v[78:79], 0, s[40:41]
	v_lshlrev_b32_e32 v148, 4, v50
	v_lshl_add_u64 v[48:49], v[48:49], 0, v[148:149]
	v_mul_u32_u24_e32 v173, 0x90, v134
	s_mov_b32 s21, 1
	v_mov_b32_e32 v158, v48
	s_mov_b32 s42, 2
	s_mov_b32 s43, 1
	s_waitcnt lgkmcnt(0)
	s_barrier
	s_mov_b64 s[98:99], s[28:29]
	s_mov_b64 s[100:101], s[30:31]
	v_add_u32_e32 v244, v174, v175
	v_add_u32_e32 v245, v171, v172
	global_load_dwordx4 v[104:107], v154, s[98:99]
	s_mov_b64 exec, s[8:9]
	global_load_dwordx4 v[108:111], v156, s[98:99]
	s_mov_b64 exec, -1
	global_load_dwordx4 v[112:115], v158, s[100:101]
	s_add_u32 s98, s98, 0x18000
	s_addc_u32 s99, s99, 0
	s_add_u32 s100, s100, 0x80
	s_addc_u32 s101, s101, 0
	s_branch .Lmla_odd

.Lmla_odd:
	ds_read_b128 v[48:51], v169 offset:13312
	ds_read_b128 v[52:55], v169 offset:13344
	ds_read_b128 v[116:119], v169 offset:19968
	ds_read_b128 v[120:123], v169 offset:20000
	s_waitcnt lgkmcnt(3)
	v_mfma_f32_32x32x16_bf16 v[64:79], v[48:51], v[100:103], v[32:47]
	ds_read_b128 v[124:127], v169 offset:13376
	ds_read_b128 v[128:131], v169 offset:13408
	ds_read_b128 v[132:135], v169 offset:20032
	ds_read_b128 v[136:139], v169 offset:20064
	s_waitcnt lgkmcnt(4)
	v_mfma_f32_32x32x16_bf16 v[64:79], v[52:55], v[96:99], v[64:79]
	v_mfma_f32_32x32x16_bf16 v[48:63], v[116:119], v[100:103], v[32:47]
	v_mfma_f32_32x32x16_bf16 v[48:63], v[120:123], v[96:99], v[48:63]
	s_waitcnt lgkmcnt(1)
	v_mfma_f32_32x32x16_bf16 v[64:79], v[124:127], v[92:95], v[64:79]
	v_mfma_f32_32x32x16_bf16 v[48:63], v[132:135], v[92:95], v[48:63]
	v_mfma_f32_32x32x16_bf16 v[64:79], v[128:131], v[88:91], v[64:79]
	ds_read_b128 v[116:119], v169 offset:13440
	ds_read_b128 v[120:123], v169 offset:13472
	ds_read_b128 v[128:131], v169 offset:20096
	ds_read_b128 v[176:179], v169 offset:20128
	s_waitcnt lgkmcnt(3)
	v_mfma_f32_32x32x16_bf16 v[48:63], v[136:139], v[88:91], v[48:63]
	v_mfma_f32_32x32x16_bf16 v[64:79], v[116:119], v[84:87], v[64:79]
	s_mulk_i32 s21, 0x2400
	v_add_u32_e32 v116, s21, v170
	ds_read_b128 v[136:139], v116 offset:26624
	ds_read_b128 v[124:127], v116 offset:26656
	s_waitcnt lgkmcnt(3)
	v_mfma_f32_32x32x16_bf16 v[48:63], v[128:131], v[84:87], v[48:63]
	v_mfma_f32_32x32x16_bf16 v[64:79], v[120:123], v[80:83], v[64:79]
	ds_read_b128 v[132:135], v116 offset:26688
	ds_read_b128 v[120:123], v116 offset:26720
	ds_read_b128 v[144:147], v116 offset:31232
	ds_read_b128 v[140:143], v116 offset:31264
	ds_read_b128 v[128:131], v116 offset:31296
	ds_read_b128 v[116:119], v116 offset:31328
	s_waitcnt lgkmcnt(8)
	v_mfma_f32_32x32x16_bf16 v[48:63], v[176:179], v[80:83], v[48:63]
	s_add_i32 s43, s43, 1
	s_nop 10
	v_max_f32_e32 v148, v64, v48
	v_max_f32_e32 v160, v65, v49
	v_max_f32_e32 v161, v67, v51
	v_max3_f32 v176, v66, v50, v70
	v_max3_f32 v161, v161, v71, v55
	v_max3_f32 v148, v148, v68, v52
	v_max3_f32 v160, v160, v69, v53
	v_max3_f32 v176, v176, v54, v74
	v_max3_f32 v161, v161, v75, v59
	v_max3_f32 v148, v148, v72, v56
	v_max3_f32 v160, v160, v73, v57
	v_max3_f32 v176, v176, v58, v78
	v_max3_f32 v161, v161, v79, v63
	v_max3_f32 v148, v148, v76, v60
	v_max3_f32 v160, v160, v77, v61
	v_max3_f32 v161, v176, v62, v161
	v_max3_f32 v148, v148, v160, v161
	v_mov_b32_e32 v160, v148
	s_nop 1
	v_permlane32_swap_b32_e32 v148, v160
	v_max_f32_e32 v148, v148, v160
	v_cmp_lt_f32_e32 vcc, s59, v148
	s_cbranch_vccz .Lmla_norescale_o
	v_max_f32_e32 v32, v148, v148
	v_max_f32_e32 v148, 0, v32
	v_exp_f32_e64 v160, -v148
	v_add_f32_e32 v168, v168, v148
	v_xor_b32_e32 v32, 0x80000000, v168
	v_mov_b32_e32 v33, v32
	v_mov_b32_e32 v34, v32
	v_mov_b32_e32 v35, v32
	v_mov_b32_e32 v36, v32
	v_mov_b32_e32 v37, v32
	v_mov_b32_e32 v38, v32
	v_mov_b32_e32 v39, v32
	v_mov_b32_e32 v40, v32
	v_mov_b32_e32 v41, v32
	v_mov_b32_e32 v42, v32
	v_mov_b32_e32 v43, v32
	v_mov_b32_e32 v44, v32
	v_mov_b32_e32 v45, v32
	v_mov_b32_e32 v46, v32
	v_mov_b32_e32 v47, v32
	v_pk_add_f32 v[64:65], v[64:65], v[148:149] op_sel_hi:[1,0] neg_lo:[0,1] neg_hi:[0,1]
	v_pk_add_f32 v[48:49], v[48:49], v[148:149] op_sel_hi:[1,0] neg_lo:[0,1] neg_hi:[0,1]
	v_pk_add_f32 v[66:67], v[66:67], v[148:149] op_sel_hi:[1,0] neg_lo:[0,1] neg_hi:[0,1]
	v_pk_add_f32 v[50:51], v[50:51], v[148:149] op_sel_hi:[1,0] neg_lo:[0,1] neg_hi:[0,1]
	v_pk_add_f32 v[68:69], v[68:69], v[148:149] op_sel_hi:[1,0] neg_lo:[0,1] neg_hi:[0,1]
	v_pk_add_f32 v[52:53], v[52:53], v[148:149] op_sel_hi:[1,0] neg_lo:[0,1] neg_hi:[0,1]
	v_pk_add_f32 v[70:71], v[70:71], v[148:149] op_sel_hi:[1,0] neg_lo:[0,1] neg_hi:[0,1]
	v_pk_add_f32 v[54:55], v[54:55], v[148:149] op_sel_hi:[1,0] neg_lo:[0,1] neg_hi:[0,1]
	v_pk_add_f32 v[72:73], v[72:73], v[148:149] op_sel_hi:[1,0] neg_lo:[0,1] neg_hi:[0,1]
	v_pk_add_f32 v[56:57], v[56:57], v[148:149] op_sel_hi:[1,0] neg_lo:[0,1] neg_hi:[0,1]
	v_pk_add_f32 v[74:75], v[74:75], v[148:149] op_sel_hi:[1,0] neg_lo:[0,1] neg_hi:[0,1]
	v_pk_add_f32 v[58:59], v[58:59], v[148:149] op_sel_hi:[1,0] neg_lo:[0,1] neg_hi:[0,1]
	v_pk_add_f32 v[76:77], v[76:77], v[148:149] op_sel_hi:[1,0] neg_lo:[0,1] neg_hi:[0,1]
	v_pk_add_f32 v[60:61], v[60:61], v[148:149] op_sel_hi:[1,0] neg_lo:[0,1] neg_hi:[0,1]
	v_pk_add_f32 v[78:79], v[78:79], v[148:149] op_sel_hi:[1,0] neg_lo:[0,1] neg_hi:[0,1]
	v_pk_add_f32 v[62:63], v[62:63], v[148:149] op_sel_hi:[1,0] neg_lo:[0,1] neg_hi:[0,1]
	v_pk_mul_f32 v[30:31], v[30:31], v[160:161] op_sel_hi:[1,0]
	v_pk_mul_f32 v[28:29], v[28:29], v[160:161] op_sel_hi:[1,0]
	v_pk_mul_f32 v[26:27], v[26:27], v[160:161] op_sel_hi:[1,0]
	v_pk_mul_f32 v[24:25], v[24:25], v[160:161] op_sel_hi:[1,0]
	v_pk_mul_f32 v[22:23], v[22:23], v[160:161] op_sel_hi:[1,0]
	v_pk_mul_f32 v[20:21], v[20:21], v[160:161] op_sel_hi:[1,0]
	v_pk_mul_f32 v[18:19], v[18:19], v[160:161] op_sel_hi:[1,0]
	v_pk_mul_f32 v[16:17], v[16:17], v[160:161] op_sel_hi:[1,0]
	v_pk_mul_f32 v[14:15], v[14:15], v[160:161] op_sel_hi:[1,0]
	v_pk_mul_f32 v[12:13], v[12:13], v[160:161] op_sel_hi:[1,0]
	v_pk_mul_f32 v[10:11], v[10:11], v[160:161] op_sel_hi:[1,0]
	v_pk_mul_f32 v[8:9], v[8:9], v[160:161] op_sel_hi:[1,0]
	v_pk_mul_f32 v[6:7], v[6:7], v[160:161] op_sel_hi:[1,0]
	v_pk_mul_f32 v[4:5], v[4:5], v[160:161] op_sel_hi:[1,0]
	v_pk_mul_f32 v[2:3], v[2:3], v[160:161] op_sel_hi:[1,0]
	v_pk_mul_f32 v[0:1], v[0:1], v[160:161] op_sel_hi:[1,0]
	v_pk_mul_f32 v[152:153], v[152:153], v[160:161] op_sel_hi:[1,0]
	v_pk_mul_f32 v[150:151], v[150:151], v[160:161] op_sel_hi:[1,0]
; #define AT_QK_LD0(kb_) do { if constexpr (NEGM) { const LAS unsigned char* kbp_ = Kl + (kb_) * KBUF + r32 * KROWB + hi * 16; AT_KLD2(0); __builtin_amdgcn_sched_barrier(0); } } while (0)
; template <int DQK, int DV, int RH, bool NEGM> ...
;     ...
;     const int NT = nkv / 64;
;     AT_GLOAD(0); AT_LSTORE(0, 0); __syncthreads();
;     int vs_prev = 2, vs_cur = 0, vs_next = 1;
;     if (!grpB) {
;         for (int t = 0; t < NT; ++t) {
;             const int kb = t & 1;
;             if (t + 1 < NT) AT_GLOAD(t + 1);
;             f32x16 p[RH][2];
;             AT_QK_LD0(kb); AT_QK(kb); AT_VLOAD(vs_cur); AT_SOFTMAX(); AT_PV(vs_cur);
;             if (t + 1 < NT) AT_LSTORE(kb ^ 1, vs_next);
;             __syncthreads();
.Lmla_norescale_o:
	v_exp_f32_e32 v160, v64
	v_exp_f32_e32 v161, v65
	v_exp_f32_e32 v64, v66
	v_exp_f32_e32 v65, v67
	v_exp_f32_e32 v68, v68
	v_exp_f32_e32 v69, v69
	v_exp_f32_e32 v66, v70
	v_exp_f32_e32 v67, v71
	v_cvt_pk_bf16_f32 v176, v160, v161
	v_cvt_pk_bf16_f32 v177, v64, v65
	v_cvt_pk_bf16_f32 v178, v68, v69
	v_cvt_pk_bf16_f32 v179, v66, v67
	v_exp_f32_e32 v70, v74
	v_exp_f32_e32 v71, v75
	s_waitcnt lgkmcnt(0)
	v_mfma_f32_32x32x16_bf16 v[16:31], v[136:139], v[176:179], v[16:31]
	v_exp_f32_e32 v136, v72
	v_exp_f32_e32 v137, v73
	v_exp_f32_e32 v74, v76
	v_exp_f32_e32 v75, v77
	v_exp_f32_e32 v72, v78
	v_exp_f32_e32 v73, v79
	v_exp_f32_e32 v76, v48
	v_mfma_f32_32x32x16_bf16 v[0:15], v[144:147], v[176:179], v[0:15]
	v_cvt_pk_bf16_f32 v144, v136, v137
	v_cvt_pk_bf16_f32 v145, v70, v71
	v_cvt_pk_bf16_f32 v146, v74, v75
	v_cvt_pk_bf16_f32 v147, v72, v73
	v_exp_f32_e32 v77, v49
	v_exp_f32_e32 v48, v50
	v_exp_f32_e32 v49, v51
	v_mfma_f32_32x32x16_bf16 v[16:31], v[124:127], v[144:147], v[16:31]
	v_exp_f32_e32 v52, v52
	v_exp_f32_e32 v53, v53
	v_exp_f32_e32 v50, v54
	v_exp_f32_e32 v51, v55
	v_cvt_pk_bf16_f32 v124, v76, v77
	v_cvt_pk_bf16_f32 v125, v48, v49
	v_cvt_pk_bf16_f32 v126, v52, v53
	v_mfma_f32_32x32x16_bf16 v[0:15], v[140:143], v[144:147], v[0:15]
	v_cvt_pk_bf16_f32 v127, v50, v51
	v_exp_f32_e32 v78, v56
	v_exp_f32_e32 v79, v57
	v_exp_f32_e32 v54, v58
	v_exp_f32_e32 v55, v59
	v_exp_f32_e32 v58, v60
	v_exp_f32_e32 v59, v61
	v_mfma_f32_32x32x16_bf16 v[16:31], v[132:135], v[124:127], v[16:31]
	v_exp_f32_e32 v56, v62
	v_exp_f32_e32 v57, v63
	v_cvt_pk_bf16_f32 v60, v78, v79
	v_cvt_pk_bf16_f32 v61, v54, v55
	v_cvt_pk_bf16_f32 v62, v58, v59
	v_cvt_pk_bf16_f32 v63, v56, v57
	v_mfma_f32_32x32x16_bf16 v[0:15], v[128:131], v[124:127], v[0:15]
	v_mfma_f32_32x32x16_bf16 v[16:31], v[120:123], v[60:63], v[16:31]
	v_mfma_f32_32x32x16_bf16 v[0:15], v[116:119], v[60:63], v[0:15]
	s_waitcnt vmcnt(1)
	ds_write_b128 v244, v[104:107]
	s_mov_b64 exec, s[8:9]
	ds_write_b128 v245, v[108:111]
	s_mov_b64 exec, -1
	s_mul_i32 s21, s42, 0x2400
	v_add_u32_e32 v242, s21, v243
	s_waitcnt vmcnt(0)
	ds_write2_b64 v242, v[112:113], v[114:115] offset1:2
	global_load_dwordx4 v[104:107], v154, s[98:99]
	s_mov_b64 exec, s[8:9]
	global_load_dwordx4 v[108:111], v156, s[98:99]
	s_mov_b64 exec, -1
	global_load_dwordx4 v[112:115], v158, s[100:101]
	s_add_u32 s98, s98, 0x18000
	s_addc_u32 s99, s99, 0
	s_add_u32 s100, s100, 0x80
	s_addc_u32 s101, s101, 0
	v_pk_add_f32 v[48:49], v[64:65], v[48:49]
	v_pk_add_f32 v[60:61], v[160:161], v[76:77]
	v_pk_add_f32 v[48:49], v[152:153], v[48:49]
	v_pk_add_f32 v[50:51], v[66:67], v[50:51]
	v_pk_add_f32 v[60:61], v[150:151], v[60:61]
	v_pk_add_f32 v[52:53], v[68:69], v[52:53]
	v_pk_add_f32 v[48:49], v[50:51], v[48:49]
	v_pk_add_f32 v[50:51], v[70:71], v[54:55]
	v_pk_add_f32 v[52:53], v[52:53], v[60:61]
	v_pk_add_f32 v[60:61], v[136:137], v[78:79]
	v_pk_add_f32 v[48:49], v[50:51], v[48:49]
	v_pk_add_f32 v[50:51], v[72:73], v[56:57]
	s_add_i32 s40, s42, 1
	v_pk_add_f32 v[52:53], v[60:61], v[52:53]
	v_pk_add_f32 v[58:59], v[74:75], v[58:59]
	v_pk_add_f32 v[152:153], v[50:51], v[48:49]
	s_cmp_lg_u32 s42, 2
	v_pk_add_f32 v[150:151], v[58:59], v[52:53]
	s_cselect_b32 s40, s40, 0
	s_cmp_lg_u32 s43, 63
	s_waitcnt lgkmcnt(0)
	s_barrier
	s_mov_b32 s21, s42
	s_mov_b32 s42, s40
	ds_read_b128 v[48:51], v169
	ds_read_b128 v[52:55], v169 offset:32
	ds_read_b128 v[116:119], v169 offset:6656
	ds_read_b128 v[120:123], v169 offset:6688
	s_waitcnt lgkmcnt(3)
	v_mfma_f32_32x32x16_bf16 v[64:79], v[48:51], v[100:103], v[32:47]
	ds_read_b128 v[124:127], v169 offset:64
	ds_read_b128 v[128:131], v169 offset:96
	ds_read_b128 v[132:135], v169 offset:6720
	ds_read_b128 v[136:139], v169 offset:6752
	s_waitcnt lgkmcnt(4)
	v_mfma_f32_32x32x16_bf16 v[64:79], v[52:55], v[96:99], v[64:79]
	v_mfma_f32_32x32x16_bf16 v[48:63], v[116:119], v[100:103], v[32:47]
	v_mfma_f32_32x32x16_bf16 v[48:63], v[120:123], v[96:99], v[48:63]
	s_waitcnt lgkmcnt(1)
	v_mfma_f32_32x32x16_bf16 v[64:79], v[124:127], v[92:95], v[64:79]
	v_mfma_f32_32x32x16_bf16 v[48:63], v[132:135], v[92:95], v[48:63]
	v_mfma_f32_32x32x16_bf16 v[64:79], v[128:131], v[88:91], v[64:79]
	ds_read_b128 v[116:119], v169 offset:128
	ds_read_b128 v[120:123], v169 offset:160
	ds_read_b128 v[128:131], v169 offset:6784
	ds_read_b128 v[176:179], v169 offset:6816
	s_waitcnt lgkmcnt(3)
	v_mfma_f32_32x32x16_bf16 v[48:63], v[136:139], v[88:91], v[48:63]
	v_mfma_f32_32x32x16_bf16 v[64:79], v[116:119], v[84:87], v[64:79]
	s_mulk_i32 s21, 0x2400
	v_add_u32_e32 v116, s21, v170
	ds_read_b128 v[136:139], v116 offset:26624
	ds_read_b128 v[124:127], v116 offset:26656
	s_waitcnt lgkmcnt(3)
	v_mfma_f32_32x32x16_bf16 v[48:63], v[128:131], v[84:87], v[48:63]
	v_mfma_f32_32x32x16_bf16 v[64:79], v[120:123], v[80:83], v[64:79]
	ds_read_b128 v[132:135], v116 offset:26688
	ds_read_b128 v[120:123], v116 offset:26720
	ds_read_b128 v[144:147], v116 offset:31232
	ds_read_b128 v[140:143], v116 offset:31264
	ds_read_b128 v[128:131], v116 offset:31296
	ds_read_b128 v[116:119], v116 offset:31328
	s_waitcnt lgkmcnt(8)
	v_mfma_f32_32x32x16_bf16 v[48:63], v[176:179], v[80:83], v[48:63]
	s_add_i32 s43, s43, 1
	s_nop 10
	v_max_f32_e32 v148, v64, v48
	v_max_f32_e32 v160, v65, v49
	v_max_f32_e32 v161, v67, v51
	v_max3_f32 v176, v66, v50, v70
	v_max3_f32 v161, v161, v71, v55
	v_max3_f32 v148, v148, v68, v52
	v_max3_f32 v160, v160, v69, v53
	v_max3_f32 v176, v176, v54, v74
	v_max3_f32 v161, v161, v75, v59
	v_max3_f32 v148, v148, v72, v56
	v_max3_f32 v160, v160, v73, v57
	v_max3_f32 v176, v176, v58, v78
	v_max3_f32 v161, v161, v79, v63
	v_max3_f32 v148, v148, v76, v60
	v_max3_f32 v160, v160, v77, v61
	v_max3_f32 v161, v176, v62, v161
	v_max3_f32 v148, v148, v160, v161
	v_mov_b32_e32 v160, v148
	s_nop 1
	v_permlane32_swap_b32_e32 v148, v160
	v_max_f32_e32 v148, v148, v160
	v_cmp_lt_f32_e32 vcc, s59, v148
	s_cbranch_vccz .Lmla_norescale_e
; #define AT_QK_LD0(kb_) do { if constexpr (NEGM) { const LAS unsigned char* kbp_ = Kl + (kb_) * KBUF + r32 * KROWB + hi * 16; AT_KLD2(0); __builtin_amdgcn_sched_barrier(0); } } while (0)
; template <int DQK, int DV, int RH, bool NEGM> ...
;     ...
;     const int NT = nkv / 64;
;     AT_GLOAD(0); AT_LSTORE(0, 0); __syncthreads();
;     int vs_prev = 2, vs_cur = 0, vs_next = 1;
;     if (!grpB) {
;         for (int t = 0; t < NT; ++t) {
;             const int kb = t & 1;
;             if (t + 1 < NT) AT_GLOAD(t + 1);
;             f32x16 p[RH][2];
;             AT_QK_LD0(kb); AT_QK(kb); AT_VLOAD(vs_cur); AT_SOFTMAX(); AT_PV(vs_cur);
;             if (t + 1 < NT) AT_LSTORE(kb ^ 1, vs_next);
;             __syncthreads();
;             vs_prev = vs_cur; vs_cur = vs_next; vs_next = (vs_next == 2) ? 0 : vs_next + 1;
	v_max_f32_e32 v32, v148, v148
	v_max_f32_e32 v148, 0, v32
	v_exp_f32_e64 v160, -v148
	v_add_f32_e32 v168, v168, v148
	v_xor_b32_e32 v32, 0x80000000, v168
	v_mov_b32_e32 v33, v32
	v_mov_b32_e32 v34, v32
	v_mov_b32_e32 v35, v32
	v_mov_b32_e32 v36, v32
	v_mov_b32_e32 v37, v32
	v_mov_b32_e32 v38, v32
	v_mov_b32_e32 v39, v32
	v_mov_b32_e32 v40, v32
	v_mov_b32_e32 v41, v32
	v_mov_b32_e32 v42, v32
	v_mov_b32_e32 v43, v32
	v_mov_b32_e32 v44, v32
	v_mov_b32_e32 v45, v32
	v_mov_b32_e32 v46, v32
	v_mov_b32_e32 v47, v32
	v_pk_add_f32 v[64:65], v[64:65], v[148:149] op_sel_hi:[1,0] neg_lo:[0,1] neg_hi:[0,1]
	v_pk_add_f32 v[48:49], v[48:49], v[148:149] op_sel_hi:[1,0] neg_lo:[0,1] neg_hi:[0,1]
	v_pk_add_f32 v[66:67], v[66:67], v[148:149] op_sel_hi:[1,0] neg_lo:[0,1] neg_hi:[0,1]
	v_pk_add_f32 v[50:51], v[50:51], v[148:149] op_sel_hi:[1,0] neg_lo:[0,1] neg_hi:[0,1]
	v_pk_add_f32 v[68:69], v[68:69], v[148:149] op_sel_hi:[1,0] neg_lo:[0,1] neg_hi:[0,1]
	v_pk_add_f32 v[52:53], v[52:53], v[148:149] op_sel_hi:[1,0] neg_lo:[0,1] neg_hi:[0,1]
	v_pk_add_f32 v[70:71], v[70:71], v[148:149] op_sel_hi:[1,0] neg_lo:[0,1] neg_hi:[0,1]
	v_pk_add_f32 v[54:55], v[54:55], v[148:149] op_sel_hi:[1,0] neg_lo:[0,1] neg_hi:[0,1]
	v_pk_add_f32 v[72:73], v[72:73], v[148:149] op_sel_hi:[1,0] neg_lo:[0,1] neg_hi:[0,1]
	v_pk_add_f32 v[56:57], v[56:57], v[148:149] op_sel_hi:[1,0] neg_lo:[0,1] neg_hi:[0,1]
	v_pk_add_f32 v[74:75], v[74:75], v[148:149] op_sel_hi:[1,0] neg_lo:[0,1] neg_hi:[0,1]
	v_pk_add_f32 v[58:59], v[58:59], v[148:149] op_sel_hi:[1,0] neg_lo:[0,1] neg_hi:[0,1]
	v_pk_add_f32 v[76:77], v[76:77], v[148:149] op_sel_hi:[1,0] neg_lo:[0,1] neg_hi:[0,1]
	v_pk_add_f32 v[60:61], v[60:61], v[148:149] op_sel_hi:[1,0] neg_lo:[0,1] neg_hi:[0,1]
	v_pk_add_f32 v[78:79], v[78:79], v[148:149] op_sel_hi:[1,0] neg_lo:[0,1] neg_hi:[0,1]
	v_pk_add_f32 v[62:63], v[62:63], v[148:149] op_sel_hi:[1,0] neg_lo:[0,1] neg_hi:[0,1]
	v_pk_mul_f32 v[30:31], v[30:31], v[160:161] op_sel_hi:[1,0]
	v_pk_mul_f32 v[28:29], v[28:29], v[160:161] op_sel_hi:[1,0]
	v_pk_mul_f32 v[26:27], v[26:27], v[160:161] op_sel_hi:[1,0]
	v_pk_mul_f32 v[24:25], v[24:25], v[160:161] op_sel_hi:[1,0]
	v_pk_mul_f32 v[22:23], v[22:23], v[160:161] op_sel_hi:[1,0]
	v_pk_mul_f32 v[20:21], v[20:21], v[160:161] op_sel_hi:[1,0]
	v_pk_mul_f32 v[18:19], v[18:19], v[160:161] op_sel_hi:[1,0]
	v_pk_mul_f32 v[16:17], v[16:17], v[160:161] op_sel_hi:[1,0]
	v_pk_mul_f32 v[14:15], v[14:15], v[160:161] op_sel_hi:[1,0]
	v_pk_mul_f32 v[12:13], v[12:13], v[160:161] op_sel_hi:[1,0]
	v_pk_mul_f32 v[10:11], v[10:11], v[160:161] op_sel_hi:[1,0]
	v_pk_mul_f32 v[8:9], v[8:9], v[160:161] op_sel_hi:[1,0]
	v_pk_mul_f32 v[6:7], v[6:7], v[160:161] op_sel_hi:[1,0]
	v_pk_mul_f32 v[4:5], v[4:5], v[160:161] op_sel_hi:[1,0]
	v_pk_mul_f32 v[2:3], v[2:3], v[160:161] op_sel_hi:[1,0]
	v_pk_mul_f32 v[0:1], v[0:1], v[160:161] op_sel_hi:[1,0]
	v_pk_mul_f32 v[152:153], v[152:153], v[160:161] op_sel_hi:[1,0]
	v_pk_mul_f32 v[150:151], v[150:151], v[160:161] op_sel_hi:[1,0]
.Lmla_norescale_e:
	v_exp_f32_e32 v160, v64
	v_exp_f32_e32 v161, v65
	v_exp_f32_e32 v64, v66
	v_exp_f32_e32 v65, v67
	v_exp_f32_e32 v68, v68
	v_exp_f32_e32 v69, v69
	v_exp_f32_e32 v66, v70
	v_exp_f32_e32 v67, v71
	v_cvt_pk_bf16_f32 v176, v160, v161
	v_cvt_pk_bf16_f32 v177, v64, v65
	v_cvt_pk_bf16_f32 v178, v68, v69
	v_cvt_pk_bf16_f32 v179, v66, v67
	v_exp_f32_e32 v70, v74
	v_exp_f32_e32 v71, v75
	s_waitcnt lgkmcnt(0)
	v_mfma_f32_32x32x16_bf16 v[16:31], v[136:139], v[176:179], v[16:31]
	v_exp_f32_e32 v136, v72
	v_exp_f32_e32 v137, v73
	v_exp_f32_e32 v74, v76
	v_exp_f32_e32 v75, v77
	v_exp_f32_e32 v72, v78
	v_exp_f32_e32 v73, v79
	v_exp_f32_e32 v76, v48
	v_mfma_f32_32x32x16_bf16 v[0:15], v[144:147], v[176:179], v[0:15]
	v_cvt_pk_bf16_f32 v144, v136, v137
	v_cvt_pk_bf16_f32 v145, v70, v71
	v_cvt_pk_bf16_f32 v146, v74, v75
	v_cvt_pk_bf16_f32 v147, v72, v73
	v_exp_f32_e32 v77, v49
	v_exp_f32_e32 v48, v50
	v_exp_f32_e32 v49, v51
	v_mfma_f32_32x32x16_bf16 v[16:31], v[124:127], v[144:147], v[16:31]
	v_exp_f32_e32 v52, v52
	v_exp_f32_e32 v53, v53
	v_exp_f32_e32 v50, v54
	v_exp_f32_e32 v51, v55
	v_cvt_pk_bf16_f32 v124, v76, v77
	v_cvt_pk_bf16_f32 v125, v48, v49
	v_cvt_pk_bf16_f32 v126, v52, v53
	v_mfma_f32_32x32x16_bf16 v[0:15], v[140:143], v[144:147], v[0:15]
	v_cvt_pk_bf16_f32 v127, v50, v51
	v_exp_f32_e32 v78, v56
	v_exp_f32_e32 v79, v57
	v_exp_f32_e32 v54, v58
	v_exp_f32_e32 v55, v59
	v_exp_f32_e32 v58, v60
	v_exp_f32_e32 v59, v61
	v_mfma_f32_32x32x16_bf16 v[16:31], v[132:135], v[124:127], v[16:31]
	v_exp_f32_e32 v56, v62
	v_exp_f32_e32 v57, v63
	v_cvt_pk_bf16_f32 v60, v78, v79
	v_cvt_pk_bf16_f32 v61, v54, v55
	v_cvt_pk_bf16_f32 v62, v58, v59
	v_cvt_pk_bf16_f32 v63, v56, v57
	v_mfma_f32_32x32x16_bf16 v[0:15], v[128:131], v[124:127], v[0:15]
	v_mfma_f32_32x32x16_bf16 v[16:31], v[120:123], v[60:63], v[16:31]
	v_mfma_f32_32x32x16_bf16 v[0:15], v[116:119], v[60:63], v[0:15]
	s_waitcnt vmcnt(1)
	ds_write_b128 v244, v[104:107] offset:13312
	s_mov_b64 exec, s[8:9]
	ds_write_b128 v245, v[108:111] offset:13312
	s_mov_b64 exec, -1
	s_mul_i32 s21, s42, 0x2400
	v_add_u32_e32 v242, s21, v243
	s_waitcnt vmcnt(0)
	ds_write2_b64 v242, v[112:113], v[114:115] offset1:2
	s_cmp_eq_u32 s43, 63
	s_cbranch_scc1 .Lmla_noload
	global_load_dwordx4 v[104:107], v154, s[98:99]
	s_mov_b64 exec, s[8:9]
	global_load_dwordx4 v[108:111], v156, s[98:99]
	s_mov_b64 exec, -1
	global_load_dwordx4 v[112:115], v158, s[100:101]
	s_add_u32 s98, s98, 0x18000
	s_addc_u32 s99, s99, 0
	s_add_u32 s100, s100, 0x80
	s_addc_u32 s101, s101, 0
; #define AT_QK_LD0(kb_) do { if constexpr (NEGM) { const LAS unsigned char* kbp_ = Kl + (kb_) * KBUF + r32 * KROWB + hi * 16; AT_KLD2(0); __builtin_amdgcn_sched_barrier(0); } } while (0)
; template <int DQK, int DV, int RH, bool NEGM> ...
;     ...
;     const int NT = nkv / 64;
;     AT_GLOAD(0); AT_LSTORE(0, 0); __syncthreads();
;     int vs_prev = 2, vs_cur = 0, vs_next = 1;
;     if (!grpB) {
;         for (int t = 0; t < NT; ++t) {
;             const int kb = t & 1;
;             if (t + 1 < NT) AT_GLOAD(t + 1);
;             f32x16 p[RH][2];
;             AT_QK_LD0(kb); AT_QK(kb); AT_VLOAD(vs_cur); AT_SOFTMAX(); AT_PV(vs_cur);
;             if (t + 1 < NT) AT_LSTORE(kb ^ 1, vs_next);
;             __syncthreads();
;             vs_prev = vs_cur; vs_cur = vs_next; vs_next = (vs_next == 2) ? 0 : vs_next + 1;
.Lmla_noload:
	v_pk_add_f32 v[48:49], v[64:65], v[48:49]
	v_pk_add_f32 v[60:61], v[160:161], v[76:77]
	v_pk_add_f32 v[48:49], v[152:153], v[48:49]
	v_pk_add_f32 v[50:51], v[66:67], v[50:51]
	v_pk_add_f32 v[60:61], v[150:151], v[60:61]
	v_pk_add_f32 v[52:53], v[68:69], v[52:53]
	v_pk_add_f32 v[48:49], v[50:51], v[48:49]
	v_pk_add_f32 v[50:51], v[70:71], v[54:55]
	v_pk_add_f32 v[52:53], v[52:53], v[60:61]
	v_pk_add_f32 v[60:61], v[136:137], v[78:79]
	v_pk_add_f32 v[48:49], v[50:51], v[48:49]
	v_pk_add_f32 v[50:51], v[72:73], v[56:57]
	s_add_i32 s40, s42, 1
	v_pk_add_f32 v[52:53], v[60:61], v[52:53]
	v_pk_add_f32 v[58:59], v[74:75], v[58:59]
	v_pk_add_f32 v[152:153], v[50:51], v[48:49]
	s_cmp_lg_u32 s42, 2
	v_pk_add_f32 v[150:151], v[58:59], v[52:53]
	s_cselect_b32 s40, s40, 0
	s_cmp_lg_u32 s43, 63
	s_waitcnt lgkmcnt(0)
	s_barrier
	s_cbranch_scc1 .Lmla_loop
	ds_read_b128 v[64:67], v169 offset:13312
	ds_read_b128 v[68:71], v169 offset:13344
	ds_read_b128 v[72:75], v169 offset:19968
	ds_read_b128 v[76:79], v169 offset:20000
	s_waitcnt lgkmcnt(3)
	v_mfma_f32_32x32x16_bf16 v[48:63], v[64:67], v[100:103], v[32:47]
	ds_read_b128 v[64:67], v169 offset:13376
	ds_read_b128 v[104:107], v169 offset:13408
	ds_read_b128 v[108:111], v169 offset:20032
	ds_read_b128 v[112:115], v169 offset:20064
	s_waitcnt lgkmcnt(6)
	v_mfma_f32_32x32x16_bf16 v[48:63], v[68:71], v[96:99], v[48:63]
	s_waitcnt lgkmcnt(5)
	v_mfma_f32_32x32x16_bf16 v[32:47], v[72:75], v[100:103], v[32:47]
	s_waitcnt lgkmcnt(4)
	v_mfma_f32_32x32x16_bf16 v[32:47], v[76:79], v[96:99], v[32:47]
	s_waitcnt lgkmcnt(3)
	v_mfma_f32_32x32x16_bf16 v[48:63], v[64:67], v[92:95], v[48:63]
	ds_read_b128 v[64:67], v169 offset:13440
	ds_read_b128 v[68:71], v169 offset:13472
	ds_read_b128 v[72:75], v169 offset:20096
	ds_read_b128 v[76:79], v169 offset:20128
	s_waitcnt lgkmcnt(5)
	v_mfma_f32_32x32x16_bf16 v[32:47], v[108:111], v[92:95], v[32:47]
	v_mfma_f32_32x32x16_bf16 v[48:63], v[104:107], v[88:91], v[48:63]
	s_waitcnt lgkmcnt(4)
	v_mfma_f32_32x32x16_bf16 v[32:47], v[112:115], v[88:91], v[32:47]
	s_waitcnt lgkmcnt(3)
	v_mfma_f32_32x32x16_bf16 v[48:63], v[64:67], v[84:87], v[48:63]
	v_add3_u32 v64, v167, s21, v173
	v_add_u32_e32 v65, 0x6800, v64
	ds_read_b128 v[108:111], v65
	ds_read_b128 v[104:107], v65 offset:32
	ds_read_b128 v[96:99], v65 offset:64
	ds_read_b128 v[88:91], v65 offset:96
	s_waitcnt lgkmcnt(5)
	v_mfma_f32_32x32x16_bf16 v[32:47], v[72:75], v[84:87], v[32:47]
	ds_read_b128 v[112:115], v65 offset:4608
	ds_read_b128 v[100:103], v65 offset:4640
	ds_read_b128 v[92:95], v65 offset:4672
	ds_read_b128 v[84:87], v65 offset:4704
	v_mfma_f32_32x32x16_bf16 v[48:63], v[68:71], v[80:83], v[48:63]
	s_waitcnt lgkmcnt(8)
	v_mfma_f32_32x32x16_bf16 v[32:47], v[76:79], v[80:83], v[32:47]
	s_nop 11
	v_max_f32_e32 v64, v32, v32
	v_max_f32_e32 v65, v48, v48
	v_max_f32_e32 v64, v65, v64
	v_max_f32_e32 v65, v33, v33
	v_max_f32_e32 v66, v49, v49
	v_max_f32_e32 v65, v66, v65
	v_max_f32_e32 v66, v35, v35
	v_max_f32_e32 v67, v51, v51
	v_max_f32_e32 v66, v67, v66
	v_max3_f32 v67, v50, v34, v54
	v_max3_f32 v66, v66, v55, v39
	v_max3_f32 v64, v64, v52, v36
	v_max3_f32 v65, v65, v53, v37
	v_max3_f32 v67, v67, v38, v58
	v_max3_f32 v66, v66, v59, v43
	v_max3_f32 v64, v64, v56, v40
	v_max3_f32 v65, v65, v57, v41
	v_max3_f32 v67, v67, v42, v62
	v_max3_f32 v66, v66, v63, v47
	v_max3_f32 v64, v64, v60, v44
	v_max3_f32 v65, v65, v61, v45
	v_max3_f32 v66, v67, v46, v66
	v_max3_f32 v64, v64, v65, v66
	v_mov_b32_e32 v65, v64
	s_nop 1
	v_permlane32_swap_b32_e32 v64, v65
	v_max_f32_e32 v65, v65, v65
	v_max_f32_e32 v64, v64, v64
	v_max_f32_e32 v64, v64, v65
	v_cmp_lt_f32_e32 vcc, s59, v64
	s_cbranch_vccnz .LBB0_861
	v_mov_b32_e32 v64, v151
	v_mov_b32_e32 v151, v152
	v_mov_b32_e32 v65, v153
	s_branch .LBB0_862
